# v87_state_scan_stores_write_through_sc1
# speedup vs baseline: 1.0060x; 1.0060x over previous
; #define X make_ctx(lds_raw)
;     ...
;     for (int gid = X.gtid; gid < 131072; gid += X.nthr) {
;         const int bh = gid >> 13, e4 = gid & 8191, d4 = (e4 & 31) * 4;
;         f32x4 S = {0.f, 0.f, 0.f, 0.f};
;         u32x2 kv[32];
; #pragma unroll
;         for (int j = 0; j < 32; ++j) kv[j] = kb[(size_t)(bh * 32 + j) * 8192 + e4];
; #pragma unroll
;         for (int hb = 0; hb < 2; ++hb) {
;             f32x4 dc[16];
; #pragma unroll
;             for (int j = 0; j < 16; ++j) dc[j] = *(const f32x4*)(decb + (bh * 32 + hb * 16 + j) * 128 + d4);
.LBB0_397:
	v_ashrrev_i32_e32 v164, 8, v162
	v_and_b32_e32 v0, 0x1fff, v162
	v_and_b32_e32 v130, 0xffffffe0, v164
	v_lshlrev_b32_e32 v0, 3, v0
	v_ashrrev_i32_e32 v131, 31, v130
	v_or_b32_e32 v132, 1, v130
	v_lshl_add_u64 v[2:3], s[4:5], 0, v[0:1]
	v_lshlrev_b64 v[4:5], 16, v[130:131]
	v_ashrrev_i32_e32 v133, 31, v132
	v_or_b32_e32 v134, 2, v130
	v_lshl_add_u64 v[128:129], v[2:3], 0, v[4:5]
	v_lshlrev_b64 v[4:5], 16, v[132:133]
	v_ashrrev_i32_e32 v135, 31, v134
	v_or_b32_e32 v136, 3, v130
	v_lshl_add_u64 v[124:125], v[2:3], 0, v[4:5]
	v_lshlrev_b64 v[4:5], 16, v[134:135]
	v_ashrrev_i32_e32 v137, 31, v136
	v_or_b32_e32 v138, 4, v130
	v_lshl_add_u64 v[120:121], v[2:3], 0, v[4:5]
	v_lshlrev_b64 v[4:5], 16, v[136:137]
	v_ashrrev_i32_e32 v139, 31, v138
	v_or_b32_e32 v140, 5, v130
	v_lshl_add_u64 v[116:117], v[2:3], 0, v[4:5]
	v_lshlrev_b64 v[4:5], 16, v[138:139]
	v_ashrrev_i32_e32 v141, 31, v140
	v_or_b32_e32 v142, 6, v130
	v_lshl_add_u64 v[112:113], v[2:3], 0, v[4:5]
	v_lshlrev_b64 v[4:5], 16, v[140:141]
	v_ashrrev_i32_e32 v143, 31, v142
	v_or_b32_e32 v144, 7, v130
	v_lshl_add_u64 v[108:109], v[2:3], 0, v[4:5]
	v_lshlrev_b64 v[4:5], 16, v[142:143]
	v_ashrrev_i32_e32 v145, 31, v144
	v_or_b32_e32 v146, 8, v130
	v_lshl_add_u64 v[104:105], v[2:3], 0, v[4:5]
	v_lshlrev_b64 v[4:5], 16, v[144:145]
	v_ashrrev_i32_e32 v147, 31, v146
	v_or_b32_e32 v148, 9, v130
	v_lshl_add_u64 v[100:101], v[2:3], 0, v[4:5]
	v_lshlrev_b64 v[4:5], 16, v[146:147]
	v_ashrrev_i32_e32 v149, 31, v148
	v_or_b32_e32 v150, 10, v130
	v_lshl_add_u64 v[96:97], v[2:3], 0, v[4:5]
	v_lshlrev_b64 v[4:5], 16, v[148:149]
	v_ashrrev_i32_e32 v151, 31, v150
	v_or_b32_e32 v152, 11, v130
	v_lshl_add_u64 v[92:93], v[2:3], 0, v[4:5]
	v_lshlrev_b64 v[4:5], 16, v[150:151]
	v_ashrrev_i32_e32 v153, 31, v152
	v_or_b32_e32 v154, 12, v130
	v_lshl_add_u64 v[88:89], v[2:3], 0, v[4:5]
	v_lshlrev_b64 v[4:5], 16, v[152:153]
	v_ashrrev_i32_e32 v155, 31, v154
	v_or_b32_e32 v156, 13, v130
	v_lshl_add_u64 v[84:85], v[2:3], 0, v[4:5]
	v_lshlrev_b64 v[4:5], 16, v[154:155]
	v_ashrrev_i32_e32 v157, 31, v156
	v_or_b32_e32 v158, 14, v130
	v_lshl_add_u64 v[80:81], v[2:3], 0, v[4:5]
	v_lshlrev_b64 v[4:5], 16, v[156:157]
	v_ashrrev_i32_e32 v159, 31, v158
	v_or_b32_e32 v160, 15, v130
	v_lshl_add_u64 v[76:77], v[2:3], 0, v[4:5]
	v_lshlrev_b64 v[4:5], 16, v[158:159]
	v_ashrrev_i32_e32 v161, 31, v160
	v_or_b32_e32 v64, 16, v130
	v_lshl_add_u64 v[72:73], v[2:3], 0, v[4:5]
	v_lshlrev_b64 v[4:5], 16, v[160:161]
	v_ashrrev_i32_e32 v65, 31, v64
	v_lshl_add_u64 v[68:69], v[2:3], 0, v[4:5]
	v_lshlrev_b64 v[4:5], 16, v[64:65]
	v_lshl_add_u64 v[62:63], v[2:3], 0, v[4:5]
	v_or_b32_e32 v4, 17, v130
	v_ashrrev_i32_e32 v5, 31, v4
	v_lshlrev_b64 v[4:5], 16, v[4:5]
	v_lshl_add_u64 v[58:59], v[2:3], 0, v[4:5]
	v_or_b32_e32 v4, 18, v130
	v_ashrrev_i32_e32 v5, 31, v4
	v_lshlrev_b64 v[4:5], 16, v[4:5]
	v_lshl_add_u64 v[54:55], v[2:3], 0, v[4:5]
	v_or_b32_e32 v4, 19, v130
	v_ashrrev_i32_e32 v5, 31, v4
	v_lshlrev_b64 v[4:5], 16, v[4:5]
	v_lshl_add_u64 v[50:51], v[2:3], 0, v[4:5]
	v_or_b32_e32 v4, 20, v130
	v_ashrrev_i32_e32 v5, 31, v4
	v_lshlrev_b64 v[4:5], 16, v[4:5]
	v_lshl_add_u64 v[46:47], v[2:3], 0, v[4:5]
	v_or_b32_e32 v4, 21, v130
	v_ashrrev_i32_e32 v5, 31, v4
	v_lshlrev_b64 v[4:5], 16, v[4:5]
	v_lshl_add_u64 v[42:43], v[2:3], 0, v[4:5]
	v_or_b32_e32 v4, 22, v130
	v_ashrrev_i32_e32 v5, 31, v4
	v_lshlrev_b64 v[4:5], 16, v[4:5]
	v_lshl_add_u64 v[38:39], v[2:3], 0, v[4:5]
	v_or_b32_e32 v4, 23, v130
	v_ashrrev_i32_e32 v5, 31, v4
	v_lshlrev_b64 v[4:5], 16, v[4:5]
	v_lshl_add_u64 v[34:35], v[2:3], 0, v[4:5]
	v_or_b32_e32 v4, 24, v130
	v_ashrrev_i32_e32 v5, 31, v4
	v_lshlrev_b64 v[4:5], 16, v[4:5]
	v_lshl_add_u64 v[30:31], v[2:3], 0, v[4:5]
	v_or_b32_e32 v4, 25, v130
	v_ashrrev_i32_e32 v5, 31, v4
	v_lshlrev_b64 v[4:5], 16, v[4:5]
	v_lshl_add_u64 v[26:27], v[2:3], 0, v[4:5]
	v_or_b32_e32 v4, 26, v130
	v_ashrrev_i32_e32 v5, 31, v4
	v_lshlrev_b64 v[4:5], 16, v[4:5]
	v_lshl_add_u64 v[22:23], v[2:3], 0, v[4:5]
	v_or_b32_e32 v4, 27, v130
	v_ashrrev_i32_e32 v5, 31, v4
	v_lshlrev_b64 v[4:5], 16, v[4:5]
	v_lshl_add_u64 v[18:19], v[2:3], 0, v[4:5]
	v_or_b32_e32 v4, 28, v130
	v_ashrrev_i32_e32 v5, 31, v4
	v_lshlrev_b64 v[4:5], 16, v[4:5]
	v_lshl_add_u64 v[14:15], v[2:3], 0, v[4:5]
	v_or_b32_e32 v4, 29, v130
	v_ashrrev_i32_e32 v5, 31, v4
	v_lshlrev_b64 v[4:5], 16, v[4:5]
	v_and_b32_e32 v0, 0x7c, v163
	v_lshl_add_u64 v[10:11], v[2:3], 0, v[4:5]
	v_or_b32_e32 v4, 30, v130
	v_lshlrev_b32_e32 v0, 2, v0
	v_lshlrev_b32_e32 v130, 7, v130
	v_lshl_add_u64 v[184:185], s[6:7], 0, v[0:1]
	v_ashrrev_i32_e32 v131, 31, v130
	global_load_dwordx2 v[126:127], v[128:129], off
	global_load_dwordx2 v[122:123], v[124:125], off
	global_load_dwordx2 v[118:119], v[120:121], off
	global_load_dwordx2 v[114:115], v[116:117], off
	v_lshl_add_u64 v[188:189], v[130:131], 2, v[184:185]
	global_load_dwordx4 v[168:171], v[188:189], off
	v_lshlrev_b32_e32 v130, 7, v132
	v_ashrrev_i32_e32 v131, 31, v130
	v_lshl_add_u64 v[130:131], v[130:131], 2, v[184:185]
	global_load_dwordx4 v[130:133], v[130:131], off
	v_lshlrev_b32_e32 v134, 7, v134
	v_ashrrev_i32_e32 v135, 31, v134
	v_lshl_add_u64 v[134:135], v[134:135], 2, v[184:185]
	global_load_dwordx4 v[172:175], v[134:135], off
	v_lshlrev_b32_e32 v134, 7, v136
	v_ashrrev_i32_e32 v135, 31, v134
	v_lshl_add_u64 v[134:135], v[134:135], 2, v[184:185]
	global_load_dwordx4 v[134:137], v[134:135], off
	v_lshlrev_b32_e32 v138, 7, v138
	v_ashrrev_i32_e32 v139, 31, v138
	global_load_dwordx2 v[110:111], v[112:113], off
	global_load_dwordx2 v[106:107], v[108:109], off
	global_load_dwordx2 v[102:103], v[104:105], off
	global_load_dwordx2 v[98:99], v[100:101], off
; __device__ __forceinline__ unsigned pk2(float lo, float hi) { const f32x2 v = {lo, hi}; return __builtin_bit_cast(unsigned, __builtin_convertvector(v, bf16x2_hw)); }
; __device__ __forceinline__ float lo16(unsigned w) { return __uint_as_float(w << 16); }
; __device__ __forceinline__ float hi16(unsigned w) { return __uint_as_float(w & 0xffff0000u); }
;     ...
;         for (int j = 0; j < 32; ++j) kv[j] = kb[(size_t)(bh * 32 + j) * 8192 + e4];
; #pragma unroll
;         for (int hb = 0; hb < 2; ++hb) {
;             f32x4 dc[16];
; #pragma unroll
;             for (int j = 0; j < 16; ++j) dc[j] = *(const f32x4*)(decb + (bh * 32 + hb * 16 + j) * 128 + d4);
; #pragma unroll
;             for (int j = 0; j < 16; ++j) { const int jj = hb * 16 + j, unit = bh * 32 + jj; u32x2 wv; wv.x = pk2(S[0], S[1]); wv.y = pk2(S[2], S[3]);
;                 if (dry) *((u32x2*)(a->ws + WS_BIG + (size_t)NT * NMAIN * 2) + gid) = wv; else kb[(size_t)unit * 8192 + e4] = wv;
;                 const f32x4 kf = {lo16(kv[jj].x), hi16(kv[jj].x), lo16(kv[jj].y), hi16(kv[jj].y)}; S = dc[j] * S + kf; }
	v_lshl_add_u64 v[138:139], v[138:139], 2, v[184:185]
	global_load_dwordx4 v[176:179], v[138:139], off
	v_lshlrev_b32_e32 v138, 7, v140
	v_ashrrev_i32_e32 v139, 31, v138
	v_lshl_add_u64 v[138:139], v[138:139], 2, v[184:185]
	global_load_dwordx4 v[138:141], v[138:139], off
	v_lshlrev_b32_e32 v142, 7, v142
	v_ashrrev_i32_e32 v143, 31, v142
	v_lshl_add_u64 v[142:143], v[142:143], 2, v[184:185]
	global_load_dwordx4 v[180:183], v[142:143], off
	v_lshlrev_b32_e32 v142, 7, v144
	v_ashrrev_i32_e32 v143, 31, v142
	v_lshl_add_u64 v[142:143], v[142:143], 2, v[184:185]
	global_load_dwordx4 v[142:145], v[142:143], off
	v_lshlrev_b32_e32 v146, 7, v146
	v_ashrrev_i32_e32 v147, 31, v146
	global_load_dwordx2 v[94:95], v[96:97], off
	global_load_dwordx2 v[90:91], v[92:93], off
	global_load_dwordx2 v[86:87], v[88:89], off
	global_load_dwordx2 v[82:83], v[84:85], off
	v_lshl_add_u64 v[146:147], v[146:147], 2, v[184:185]
	global_load_dwordx4 v[192:195], v[146:147], off
	v_lshlrev_b32_e32 v146, 7, v148
	v_ashrrev_i32_e32 v147, 31, v146
	v_lshl_add_u64 v[146:147], v[146:147], 2, v[184:185]
	global_load_dwordx4 v[146:149], v[146:147], off
	v_lshlrev_b32_e32 v150, 7, v150
	v_ashrrev_i32_e32 v151, 31, v150
	v_lshl_add_u64 v[150:151], v[150:151], 2, v[184:185]
	global_load_dwordx4 v[196:199], v[150:151], off
	v_lshlrev_b32_e32 v150, 7, v152
	v_ashrrev_i32_e32 v151, 31, v150
	v_lshl_add_u64 v[150:151], v[150:151], 2, v[184:185]
	global_load_dwordx4 v[150:153], v[150:151], off
	v_lshlrev_b32_e32 v154, 7, v154
	v_ashrrev_i32_e32 v155, 31, v154
	global_load_dwordx2 v[78:79], v[80:81], off
	global_load_dwordx2 v[74:75], v[76:77], off
	global_load_dwordx2 v[70:71], v[72:73], off
	global_load_dwordx2 v[66:67], v[68:69], off
	v_lshl_add_u64 v[154:155], v[154:155], 2, v[184:185]
	global_load_dwordx4 v[200:203], v[154:155], off
	v_lshlrev_b32_e32 v154, 7, v156
	v_ashrrev_i32_e32 v155, 31, v154
	v_lshl_add_u64 v[154:155], v[154:155], 2, v[184:185]
	global_load_dwordx4 v[154:157], v[154:155], off
	v_lshlrev_b32_e32 v158, 7, v158
	v_ashrrev_i32_e32 v159, 31, v158
	v_lshl_add_u64 v[158:159], v[158:159], 2, v[184:185]
	global_load_dwordx4 v[204:207], v[158:159], off
	v_lshlrev_b32_e32 v158, 7, v160
	v_ashrrev_i32_e32 v159, 31, v158
	v_lshl_add_u64 v[158:159], v[158:159], 2, v[184:185]
	global_load_dwordx4 v[158:161], v[158:159], off
	v_lshlrev_b32_e32 v64, 7, v64
	global_store_dwordx2 v[128:129], v[166:167], off sc1
	s_waitcnt vmcnt(32)
	v_lshlrev_b32_e32 v128, 16, v126
	v_and_b32_e32 v129, 0xffff0000, v126
	v_lshlrev_b32_e32 v126, 16, v127
	v_and_b32_e32 v127, 0xffff0000, v127
	v_ashrrev_i32_e32 v65, 31, v64
	s_waitcnt vmcnt(28)
	v_pk_fma_f32 v[126:127], v[170:171], 0, v[126:127] op_sel_hi:[1,0,1]
	v_pk_fma_f32 v[128:129], v[168:169], 0, v[128:129] op_sel_hi:[1,0,1]
	v_cvt_pk_bf16_f32 v169, v126, v127
	v_cvt_pk_bf16_f32 v168, v128, v129
	global_store_dwordx2 v[124:125], v[168:169], off sc1
	v_lshlrev_b32_e32 v124, 16, v122
	v_and_b32_e32 v125, 0xffff0000, v122
	v_lshlrev_b32_e32 v122, 16, v123
	v_and_b32_e32 v123, 0xffff0000, v123
	s_waitcnt vmcnt(28)
	v_pk_fma_f32 v[122:123], v[132:133], v[126:127], v[122:123]
	v_pk_fma_f32 v[124:125], v[130:131], v[128:129], v[124:125]
	v_cvt_pk_bf16_f32 v127, v122, v123
	v_cvt_pk_bf16_f32 v126, v124, v125
	global_store_dwordx2 v[120:121], v[126:127], off sc1
	v_lshlrev_b32_e32 v120, 16, v118
	v_and_b32_e32 v121, 0xffff0000, v118
	v_lshlrev_b32_e32 v118, 16, v119
	v_and_b32_e32 v119, 0xffff0000, v119
	s_waitcnt vmcnt(28)
	v_pk_fma_f32 v[118:119], v[174:175], v[122:123], v[118:119]
	v_pk_fma_f32 v[120:121], v[172:173], v[124:125], v[120:121]
	v_cvt_pk_bf16_f32 v123, v118, v119
	v_cvt_pk_bf16_f32 v122, v120, v121
	global_store_dwordx2 v[116:117], v[122:123], off sc1
	v_lshlrev_b32_e32 v116, 16, v114
	v_and_b32_e32 v117, 0xffff0000, v114
	v_lshlrev_b32_e32 v114, 16, v115
	v_and_b32_e32 v115, 0xffff0000, v115
	s_waitcnt vmcnt(28)
	v_pk_fma_f32 v[114:115], v[136:137], v[118:119], v[114:115]
	v_pk_fma_f32 v[116:117], v[134:135], v[120:121], v[116:117]
	v_cvt_pk_bf16_f32 v119, v114, v115
	v_cvt_pk_bf16_f32 v118, v116, v117
	global_store_dwordx2 v[112:113], v[118:119], off sc1
	s_waitcnt vmcnt(28)
	v_lshlrev_b32_e32 v112, 16, v110
	v_and_b32_e32 v113, 0xffff0000, v110
	v_lshlrev_b32_e32 v110, 16, v111
	v_and_b32_e32 v111, 0xffff0000, v111
	s_waitcnt vmcnt(24)
	v_pk_fma_f32 v[110:111], v[178:179], v[114:115], v[110:111]
	v_pk_fma_f32 v[112:113], v[176:177], v[116:117], v[112:113]
	v_cvt_pk_bf16_f32 v115, v110, v111
	v_cvt_pk_bf16_f32 v114, v112, v113
	global_store_dwordx2 v[108:109], v[114:115], off sc1
	v_lshlrev_b32_e32 v108, 16, v106
	v_and_b32_e32 v109, 0xffff0000, v106
	v_lshlrev_b32_e32 v106, 16, v107
	v_and_b32_e32 v107, 0xffff0000, v107
	s_waitcnt vmcnt(24)
	v_pk_fma_f32 v[106:107], v[140:141], v[110:111], v[106:107]
	v_pk_fma_f32 v[108:109], v[138:139], v[112:113], v[108:109]
	v_cvt_pk_bf16_f32 v111, v106, v107
	v_cvt_pk_bf16_f32 v110, v108, v109
	global_store_dwordx2 v[104:105], v[110:111], off sc1
	v_lshlrev_b32_e32 v104, 16, v102
	v_and_b32_e32 v105, 0xffff0000, v102
	v_lshlrev_b32_e32 v102, 16, v103
	v_and_b32_e32 v103, 0xffff0000, v103
	s_waitcnt vmcnt(24)
	v_pk_fma_f32 v[102:103], v[182:183], v[106:107], v[102:103]
	v_pk_fma_f32 v[104:105], v[180:181], v[108:109], v[104:105]
	v_cvt_pk_bf16_f32 v107, v102, v103
	v_cvt_pk_bf16_f32 v106, v104, v105
	global_store_dwordx2 v[100:101], v[106:107], off sc1
	v_lshlrev_b32_e32 v100, 16, v98
	v_and_b32_e32 v101, 0xffff0000, v98
	v_lshlrev_b32_e32 v98, 16, v99
	v_and_b32_e32 v99, 0xffff0000, v99
	s_waitcnt vmcnt(24)
; __device__ __forceinline__ unsigned pk2(float lo, float hi) { const f32x2 v = {lo, hi}; return __builtin_bit_cast(unsigned, __builtin_convertvector(v, bf16x2_hw)); }
; __device__ __forceinline__ float lo16(unsigned w) { return __uint_as_float(w << 16); }
; __device__ __forceinline__ float hi16(unsigned w) { return __uint_as_float(w & 0xffff0000u); }
;     ...
;         for (int j = 0; j < 32; ++j) kv[j] = kb[(size_t)(bh * 32 + j) * 8192 + e4];
; #pragma unroll
;         for (int hb = 0; hb < 2; ++hb) {
;             f32x4 dc[16];
; #pragma unroll
;             for (int j = 0; j < 16; ++j) dc[j] = *(const f32x4*)(decb + (bh * 32 + hb * 16 + j) * 128 + d4);
; #pragma unroll
;             for (int j = 0; j < 16; ++j) { const int jj = hb * 16 + j, unit = bh * 32 + jj; u32x2 wv; wv.x = pk2(S[0], S[1]); wv.y = pk2(S[2], S[3]);
;                 if (dry) *((u32x2*)(a->ws + WS_BIG + (size_t)NT * NMAIN * 2) + gid) = wv; else kb[(size_t)unit * 8192 + e4] = wv;
;                 const f32x4 kf = {lo16(kv[jj].x), hi16(kv[jj].x), lo16(kv[jj].y), hi16(kv[jj].y)}; S = dc[j] * S + kf; }
	v_pk_fma_f32 v[98:99], v[144:145], v[102:103], v[98:99]
	v_pk_fma_f32 v[100:101], v[142:143], v[104:105], v[100:101]
	v_cvt_pk_bf16_f32 v103, v98, v99
	v_cvt_pk_bf16_f32 v102, v100, v101
	global_store_dwordx2 v[96:97], v[102:103], off sc1
	s_waitcnt vmcnt(24)
	v_lshlrev_b32_e32 v96, 16, v94
	v_and_b32_e32 v97, 0xffff0000, v94
	v_lshlrev_b32_e32 v94, 16, v95
	v_and_b32_e32 v95, 0xffff0000, v95
	s_waitcnt vmcnt(20)
	v_pk_fma_f32 v[94:95], v[194:195], v[98:99], v[94:95]
	v_pk_fma_f32 v[96:97], v[192:193], v[100:101], v[96:97]
	v_cvt_pk_bf16_f32 v99, v94, v95
	v_cvt_pk_bf16_f32 v98, v96, v97
	global_store_dwordx2 v[92:93], v[98:99], off sc1
	v_lshlrev_b32_e32 v92, 16, v90
	v_and_b32_e32 v93, 0xffff0000, v90
	v_lshlrev_b32_e32 v90, 16, v91
	v_and_b32_e32 v91, 0xffff0000, v91
	s_waitcnt vmcnt(20)
	v_pk_fma_f32 v[90:91], v[148:149], v[94:95], v[90:91]
	v_pk_fma_f32 v[92:93], v[146:147], v[96:97], v[92:93]
	v_cvt_pk_bf16_f32 v95, v90, v91
	v_cvt_pk_bf16_f32 v94, v92, v93
	global_store_dwordx2 v[88:89], v[94:95], off sc1
	v_lshlrev_b32_e32 v88, 16, v86
	v_and_b32_e32 v89, 0xffff0000, v86
	v_lshlrev_b32_e32 v86, 16, v87
	v_and_b32_e32 v87, 0xffff0000, v87
	s_waitcnt vmcnt(20)
	v_pk_fma_f32 v[86:87], v[198:199], v[90:91], v[86:87]
	v_pk_fma_f32 v[88:89], v[196:197], v[92:93], v[88:89]
	v_cvt_pk_bf16_f32 v91, v86, v87
	v_cvt_pk_bf16_f32 v90, v88, v89
	global_store_dwordx2 v[84:85], v[90:91], off sc1
	v_lshlrev_b32_e32 v84, 16, v82
	v_and_b32_e32 v85, 0xffff0000, v82
	v_lshlrev_b32_e32 v82, 16, v83
	v_and_b32_e32 v83, 0xffff0000, v83
	s_waitcnt vmcnt(20)
	v_pk_fma_f32 v[82:83], v[152:153], v[86:87], v[82:83]
	v_pk_fma_f32 v[84:85], v[150:151], v[88:89], v[84:85]
	v_cvt_pk_bf16_f32 v87, v82, v83
	v_cvt_pk_bf16_f32 v86, v84, v85
	global_store_dwordx2 v[80:81], v[86:87], off sc1
	s_waitcnt vmcnt(20)
	v_lshlrev_b32_e32 v80, 16, v78
	v_and_b32_e32 v81, 0xffff0000, v78
	v_lshlrev_b32_e32 v78, 16, v79
	v_and_b32_e32 v79, 0xffff0000, v79
	s_waitcnt vmcnt(16)
	v_pk_fma_f32 v[78:79], v[202:203], v[82:83], v[78:79]
	v_pk_fma_f32 v[80:81], v[200:201], v[84:85], v[80:81]
	v_cvt_pk_bf16_f32 v83, v78, v79
	v_cvt_pk_bf16_f32 v82, v80, v81
	global_store_dwordx2 v[76:77], v[82:83], off sc1
	v_lshlrev_b32_e32 v76, 16, v74
	v_and_b32_e32 v77, 0xffff0000, v74
	v_lshlrev_b32_e32 v74, 16, v75
	v_and_b32_e32 v75, 0xffff0000, v75
	s_waitcnt vmcnt(16)
	v_pk_fma_f32 v[74:75], v[156:157], v[78:79], v[74:75]
	v_pk_fma_f32 v[76:77], v[154:155], v[80:81], v[76:77]
	v_cvt_pk_bf16_f32 v79, v74, v75
	v_cvt_pk_bf16_f32 v78, v76, v77
	global_store_dwordx2 v[72:73], v[78:79], off sc1
	v_lshlrev_b32_e32 v72, 16, v70
	v_and_b32_e32 v73, 0xffff0000, v70
	v_lshlrev_b32_e32 v70, 16, v71
	v_and_b32_e32 v71, 0xffff0000, v71
	s_waitcnt vmcnt(16)
	v_pk_fma_f32 v[70:71], v[206:207], v[74:75], v[70:71]
	v_pk_fma_f32 v[72:73], v[204:205], v[76:77], v[72:73]
	v_cvt_pk_bf16_f32 v75, v70, v71
	v_cvt_pk_bf16_f32 v74, v72, v73
	global_load_dwordx2 v[60:61], v[62:63], off
	global_load_dwordx2 v[56:57], v[58:59], off
	global_load_dwordx2 v[52:53], v[54:55], off
	v_lshl_add_u64 v[64:65], v[64:65], 2, v[184:185]
	global_store_dwordx2 v[68:69], v[74:75], off sc1
	v_lshlrev_b32_e32 v68, 16, v66
	v_and_b32_e32 v69, 0xffff0000, v66
	v_lshlrev_b32_e32 v66, 16, v67
	v_and_b32_e32 v67, 0xffff0000, v67
	s_waitcnt vmcnt(19)
	v_pk_fma_f32 v[124:125], v[160:161], v[70:71], v[66:67]
	global_load_dwordx4 v[64:67], v[64:65], off
	v_ashrrev_i32_e32 v5, 31, v4
	v_lshlrev_b64 v[4:5], 16, v[4:5]
	v_add_co_u32_e32 v96, vcc, s1, v188
	global_load_dwordx2 v[48:49], v[50:51], off
	global_load_dwordx2 v[44:45], v[46:47], off
	global_load_dwordx2 v[40:41], v[42:43], off
	global_load_dwordx2 v[36:37], v[38:39], off
	v_lshl_add_u64 v[6:7], v[2:3], 0, v[4:5]
	v_addc_co_u32_e32 v97, vcc, 0, v189, vcc
	global_load_dwordx2 v[32:33], v[34:35], off
	global_load_dwordx2 v[28:29], v[30:31], off
	global_load_dwordx2 v[24:25], v[26:27], off
	global_load_dwordx2 v[20:21], v[22:23], off
	global_load_dwordx2 v[16:17], v[18:19], off
	global_load_dwordx2 v[12:13], v[14:15], off
	global_load_dwordx2 v[8:9], v[10:11], off
	global_load_dwordx2 v[4:5], v[6:7], off
	v_pk_fma_f32 v[126:127], v[158:159], v[72:73], v[68:69]
	global_load_dwordx4 v[68:71], v[96:97], off offset:512
	global_load_dwordx4 v[72:75], v[96:97], off offset:1024
	global_load_dwordx4 v[76:79], v[96:97], off offset:1536
	global_load_dwordx4 v[80:83], v[96:97], off offset:2048
	global_load_dwordx4 v[84:87], v[96:97], off offset:2560
	global_load_dwordx4 v[88:91], v[96:97], off offset:3072
	global_load_dwordx4 v[92:95], v[96:97], off offset:3584
	v_add_co_u32_e32 v120, vcc, s2, v188
	v_cvt_pk_bf16_f32 v128, v126, v127
	s_nop 0
	v_addc_co_u32_e32 v121, vcc, 0, v189, vcc
	global_load_dwordx4 v[96:99], v[120:121], off
	global_load_dwordx4 v[100:103], v[120:121], off offset:512
	global_load_dwordx4 v[104:107], v[120:121], off offset:1024
	global_load_dwordx4 v[108:111], v[120:121], off offset:1536
	global_load_dwordx4 v[112:115], v[120:121], off offset:2048
	global_load_dwordx4 v[116:119], v[120:121], off offset:2560
	s_nop 0
	global_load_dwordx4 v[120:123], v[120:121], off offset:3072
	v_cvt_pk_bf16_f32 v129, v124, v125
	global_store_dwordx2 v[62:63], v[128:129], off sc1
	v_add_u32_e32 v162, s36, v162
	v_cmp_lt_i32_e32 vcc, s3, v162
	v_add_u32_e32 v163, s0, v163
	s_or_b64 s[10:11], vcc, s[10:11]
	s_waitcnt vmcnt(31)
	v_lshlrev_b32_e32 v62, 16, v60
	v_and_b32_e32 v63, 0xffff0000, v60
	v_lshlrev_b32_e32 v60, 16, v61
	v_and_b32_e32 v61, 0xffff0000, v61
	s_waitcnt vmcnt(27)
; __device__ __forceinline__ unsigned pk2(float lo, float hi) { const f32x2 v = {lo, hi}; return __builtin_bit_cast(unsigned, __builtin_convertvector(v, bf16x2_hw)); }
; __device__ __forceinline__ float lo16(unsigned w) { return __uint_as_float(w << 16); }
; __device__ __forceinline__ float hi16(unsigned w) { return __uint_as_float(w & 0xffff0000u); }
; #define X make_ctx(lds_raw)
;     ...
;     for (int gid = X.gtid; gid < 131072; gid += X.nthr) {
;     ...
;             for (int j = 0; j < 16; ++j) { const int jj = hb * 16 + j, unit = bh * 32 + jj; u32x2 wv; wv.x = pk2(S[0], S[1]); wv.y = pk2(S[2], S[3]);
;                 if (dry) *((u32x2*)(a->ws + WS_BIG + (size_t)NT * NMAIN * 2) + gid) = wv; else kb[(size_t)unit * 8192 + e4] = wv;
;                 const f32x4 kf = {lo16(kv[jj].x), hi16(kv[jj].x), lo16(kv[jj].y), hi16(kv[jj].y)}; S = dc[j] * S + kf; }
;         }
	v_pk_fma_f32 v[60:61], v[124:125], v[66:67], v[60:61]
	v_pk_fma_f32 v[62:63], v[126:127], v[64:65], v[62:63]
	v_cvt_pk_bf16_f32 v65, v60, v61
	v_cvt_pk_bf16_f32 v64, v62, v63
	global_store_dwordx2 v[58:59], v[64:65], off sc1
	v_lshlrev_b32_e32 v58, 16, v56
	v_and_b32_e32 v59, 0xffff0000, v56
	v_lshlrev_b32_e32 v56, 16, v57
	v_and_b32_e32 v57, 0xffff0000, v57
	s_waitcnt vmcnt(15)
	v_pk_fma_f32 v[56:57], v[70:71], v[60:61], v[56:57]
	v_pk_fma_f32 v[58:59], v[68:69], v[62:63], v[58:59]
	v_cvt_pk_bf16_f32 v61, v56, v57
	v_cvt_pk_bf16_f32 v60, v58, v59
	global_store_dwordx2 v[54:55], v[60:61], off sc1
	v_lshlrev_b32_e32 v54, 16, v52
	v_and_b32_e32 v55, 0xffff0000, v52
	v_lshlrev_b32_e32 v52, 16, v53
	v_and_b32_e32 v53, 0xffff0000, v53
	s_waitcnt vmcnt(15)
	v_pk_fma_f32 v[52:53], v[74:75], v[56:57], v[52:53]
	v_pk_fma_f32 v[54:55], v[72:73], v[58:59], v[54:55]
	v_cvt_pk_bf16_f32 v57, v52, v53
	v_cvt_pk_bf16_f32 v56, v54, v55
	global_store_dwordx2 v[50:51], v[56:57], off sc1
	v_lshlrev_b32_e32 v50, 16, v48
	v_and_b32_e32 v51, 0xffff0000, v48
	v_lshlrev_b32_e32 v48, 16, v49
	v_and_b32_e32 v49, 0xffff0000, v49
	s_waitcnt vmcnt(15)
	v_pk_fma_f32 v[48:49], v[78:79], v[52:53], v[48:49]
	v_pk_fma_f32 v[50:51], v[76:77], v[54:55], v[50:51]
	v_cvt_pk_bf16_f32 v53, v48, v49
	v_cvt_pk_bf16_f32 v52, v50, v51
	global_store_dwordx2 v[46:47], v[52:53], off sc1
	v_lshlrev_b32_e32 v46, 16, v44
	v_and_b32_e32 v47, 0xffff0000, v44
	v_lshlrev_b32_e32 v44, 16, v45
	v_and_b32_e32 v45, 0xffff0000, v45
	s_waitcnt vmcnt(15)
	v_pk_fma_f32 v[44:45], v[82:83], v[48:49], v[44:45]
	v_pk_fma_f32 v[46:47], v[80:81], v[50:51], v[46:47]
	v_cvt_pk_bf16_f32 v49, v44, v45
	v_cvt_pk_bf16_f32 v48, v46, v47
	global_store_dwordx2 v[42:43], v[48:49], off sc1
	v_lshlrev_b32_e32 v42, 16, v40
	v_and_b32_e32 v43, 0xffff0000, v40
	v_lshlrev_b32_e32 v40, 16, v41
	v_and_b32_e32 v41, 0xffff0000, v41
	s_waitcnt vmcnt(15)
	v_pk_fma_f32 v[40:41], v[86:87], v[44:45], v[40:41]
	v_pk_fma_f32 v[42:43], v[84:85], v[46:47], v[42:43]
	v_cvt_pk_bf16_f32 v45, v40, v41
	v_cvt_pk_bf16_f32 v44, v42, v43
	global_store_dwordx2 v[38:39], v[44:45], off sc1
	v_lshlrev_b32_e32 v38, 16, v36
	v_and_b32_e32 v39, 0xffff0000, v36
	v_lshlrev_b32_e32 v36, 16, v37
	v_and_b32_e32 v37, 0xffff0000, v37
	s_waitcnt vmcnt(15)
	v_pk_fma_f32 v[36:37], v[90:91], v[40:41], v[36:37]
	v_pk_fma_f32 v[38:39], v[88:89], v[42:43], v[38:39]
	v_cvt_pk_bf16_f32 v41, v36, v37
	v_cvt_pk_bf16_f32 v40, v38, v39
	global_store_dwordx2 v[34:35], v[40:41], off sc1
	v_lshlrev_b32_e32 v34, 16, v32
	v_and_b32_e32 v35, 0xffff0000, v32
	v_lshlrev_b32_e32 v32, 16, v33
	v_and_b32_e32 v33, 0xffff0000, v33
	s_waitcnt vmcnt(15)
	v_pk_fma_f32 v[32:33], v[94:95], v[36:37], v[32:33]
	v_pk_fma_f32 v[34:35], v[92:93], v[38:39], v[34:35]
	v_cvt_pk_bf16_f32 v37, v32, v33
	v_cvt_pk_bf16_f32 v36, v34, v35
	global_store_dwordx2 v[30:31], v[36:37], off sc1
	v_lshlrev_b32_e32 v30, 16, v28
	v_and_b32_e32 v31, 0xffff0000, v28
	v_lshlrev_b32_e32 v28, 16, v29
	v_and_b32_e32 v29, 0xffff0000, v29
	s_waitcnt vmcnt(15)
	v_pk_fma_f32 v[28:29], v[98:99], v[32:33], v[28:29]
	v_pk_fma_f32 v[30:31], v[96:97], v[34:35], v[30:31]
	v_cvt_pk_bf16_f32 v33, v28, v29
	v_cvt_pk_bf16_f32 v32, v30, v31
	global_store_dwordx2 v[26:27], v[32:33], off sc1
	v_lshlrev_b32_e32 v26, 16, v24
	v_and_b32_e32 v27, 0xffff0000, v24
	v_lshlrev_b32_e32 v24, 16, v25
	v_and_b32_e32 v25, 0xffff0000, v25
	s_waitcnt vmcnt(15)
	v_pk_fma_f32 v[24:25], v[102:103], v[28:29], v[24:25]
	v_pk_fma_f32 v[26:27], v[100:101], v[30:31], v[26:27]
	v_cvt_pk_bf16_f32 v29, v24, v25
	v_cvt_pk_bf16_f32 v28, v26, v27
	global_store_dwordx2 v[22:23], v[28:29], off sc1
	v_lshlrev_b32_e32 v22, 16, v20
	v_and_b32_e32 v23, 0xffff0000, v20
	v_lshlrev_b32_e32 v20, 16, v21
	v_and_b32_e32 v21, 0xffff0000, v21
	s_waitcnt vmcnt(15)
	v_pk_fma_f32 v[20:21], v[106:107], v[24:25], v[20:21]
	v_pk_fma_f32 v[22:23], v[104:105], v[26:27], v[22:23]
	v_cvt_pk_bf16_f32 v25, v20, v21
	v_cvt_pk_bf16_f32 v24, v22, v23
	global_store_dwordx2 v[18:19], v[24:25], off sc1
	v_lshlrev_b32_e32 v18, 16, v16
	v_and_b32_e32 v19, 0xffff0000, v16
	v_lshlrev_b32_e32 v16, 16, v17
	v_and_b32_e32 v17, 0xffff0000, v17
	s_waitcnt vmcnt(15)
	v_pk_fma_f32 v[16:17], v[110:111], v[20:21], v[16:17]
	v_pk_fma_f32 v[18:19], v[108:109], v[22:23], v[18:19]
	v_cvt_pk_bf16_f32 v21, v16, v17
	v_cvt_pk_bf16_f32 v20, v18, v19
	global_store_dwordx2 v[14:15], v[20:21], off sc1
	v_lshlrev_b32_e32 v14, 16, v12
	v_and_b32_e32 v15, 0xffff0000, v12
	v_lshlrev_b32_e32 v12, 16, v13
	v_and_b32_e32 v13, 0xffff0000, v13
	s_waitcnt vmcnt(15)
	v_pk_fma_f32 v[12:13], v[114:115], v[16:17], v[12:13]
	v_pk_fma_f32 v[14:15], v[112:113], v[18:19], v[14:15]
	v_cvt_pk_bf16_f32 v17, v12, v13
	v_cvt_pk_bf16_f32 v16, v14, v15
	global_store_dwordx2 v[10:11], v[16:17], off sc1
	v_lshlrev_b32_e32 v10, 16, v8
	v_and_b32_e32 v11, 0xffff0000, v8
	v_lshlrev_b32_e32 v8, 16, v9
	v_and_b32_e32 v9, 0xffff0000, v9
	s_waitcnt vmcnt(15)
	v_pk_fma_f32 v[8:9], v[118:119], v[12:13], v[8:9]
	v_pk_fma_f32 v[10:11], v[116:117], v[14:15], v[10:11]
	v_cvt_pk_bf16_f32 v13, v8, v9
	v_cvt_pk_bf16_f32 v12, v10, v11
	global_store_dwordx2 v[6:7], v[12:13], off sc1
	v_lshlrev_b32_e32 v6, 16, v4
	v_and_b32_e32 v7, 0xffff0000, v4
	v_lshlrev_b32_e32 v4, 16, v5
	v_and_b32_e32 v5, 0xffff0000, v5
	s_waitcnt vmcnt(15)
	v_pk_fma_f32 v[8:9], v[122:123], v[8:9], v[4:5]
	v_pk_fma_f32 v[4:5], v[120:121], v[10:11], v[6:7]
	v_or_b32_e32 v6, 31, v164
	v_ashrrev_i32_e32 v7, 31, v6
	v_lshlrev_b64 v[6:7], 16, v[6:7]
	v_cvt_pk_bf16_f32 v4, v4, v5
	v_cvt_pk_bf16_f32 v5, v8, v9
	v_lshl_add_u64 v[2:3], v[2:3], 0, v[6:7]
	global_store_dwordx2 v[2:3], v[4:5], off sc1
	s_andn2_b64 exec, exec, s[10:11]
	s_cbranch_execnz .LBB0_397
